# phase 0 item split: mod blocks 0..191 take 1 mod item + 3 conversion tiles (stride 192), blocks 192..511 share tiles 576.. with stride 320
# speedup vs baseline: 1.0040x; 1.0040x over previous
.LBB0_81:
	s_or_b64 exec, exec, s[4:5]
	v_readlane_b32 s4, v255, 29
	v_readlane_b32 s5, v255, 30
	s_andn2_b64 vcc, exec, s[4:5]
	s_cbranch_vccnz .LBB0_76
	v_readlane_b32 s77, v255, 28
	s_add_i32 s0, s77, 0x240
	s_cmpk_lt_u32 s77, 0xc0
	s_cselect_b32 s77, s77, s0
	s_branch .LBB0_85

.LBB0_84:
	v_readlane_b32 s0, v255, 28
	s_cmpk_lt_u32 s0, 0xc0
	s_movk_i32 s78, 0x140
	s_cselect_b32 s78, 0xc0, s78
	s_movk_i32 s80, 0xc73
	s_cselect_b32 s80, 0x2ff, s80
	s_add_i32 s77, s77, s78
	s_cmp_gt_i32 s77, s80
	s_cbranch_scc1 .LBB0_76
